# GLU GEMM epilogue: bias and z loads software-pipelined four loads ahead (addresses from a pre-pass) instead of two serialized round trips per step
# baseline (speedup 1.0000x reference)
.LBB0_295:
	s_lshl_b32 s0, s0, 8
	v_mov_b32_e32 v240, v1
	v_mov_b32_e32 v241, v148
	s_or_b32 s0, s0, s90
	s_lshl_b32 s1, s38, 8
	v_lshl_add_u32 v242, v241, 3, s0
	s_add_i32 s1, s1, s75
	v_ashrrev_i32_e32 v243, 31, v242
	v_add_u32_e32 v240, s1, v240
	v_lshl_add_u64 v[244:245], v[242:243], 2, s[12:13]
	v_mov_b32_e32 v196, v244
	v_mov_b32_e32 v197, v245
	v_ashrrev_i32_e32 v241, 31, v240
	v_lshlrev_b64 v[246:247], 10, v[240:241]
	v_lshl_add_u64 v[246:247], s[8:9], 0, v[246:247]
	v_lshlrev_b64 v[248:249], 1, v[242:243]
	v_lshl_add_u64 v[250:251], v[246:247], 0, v[248:249]
	v_mov_b32_e32 v198, v250
	v_mov_b32_e32 v199, v251
	v_add_u32_e32 v242, 0x80, v242
	v_ashrrev_i32_e32 v243, 31, v242
	v_lshlrev_b64 v[242:243], 1, v[242:243]
	v_lshl_add_u64 v[246:247], v[246:247], 0, v[242:243]
	v_mov_b32_e32 v200, v246
	v_mov_b32_e32 v201, v247
	v_add_u32_e32 v246, 16, v240
	v_ashrrev_i32_e32 v247, 31, v246
	v_lshlrev_b64 v[246:247], 10, v[246:247]
	v_lshl_add_u64 v[246:247], s[8:9], 0, v[246:247]
	v_lshl_add_u64 v[250:251], v[246:247], 0, v[248:249]
	v_mov_b32_e32 v202, v250
	v_mov_b32_e32 v203, v251
	v_lshl_add_u64 v[246:247], v[246:247], 0, v[242:243]
	v_mov_b32_e32 v204, v246
	v_mov_b32_e32 v205, v247
	v_add_u32_e32 v246, 32, v240
	v_ashrrev_i32_e32 v247, 31, v246
	v_lshlrev_b64 v[246:247], 10, v[246:247]
	v_lshl_add_u64 v[246:247], s[8:9], 0, v[246:247]
	v_lshl_add_u64 v[250:251], v[246:247], 0, v[248:249]
	v_mov_b32_e32 v206, v250
	v_mov_b32_e32 v207, v251
	v_lshl_add_u64 v[246:247], v[246:247], 0, v[242:243]
	v_mov_b32_e32 v208, v246
	v_mov_b32_e32 v209, v247
	v_add_u32_e32 v246, 48, v240
	v_ashrrev_i32_e32 v247, 31, v246
	v_lshlrev_b64 v[246:247], 10, v[246:247]
	v_lshl_add_u64 v[246:247], s[8:9], 0, v[246:247]
	v_lshl_add_u64 v[250:251], v[246:247], 0, v[248:249]
	v_mov_b32_e32 v210, v250
	v_mov_b32_e32 v211, v251
	v_lshl_add_u64 v[246:247], v[246:247], 0, v[242:243]
	v_mov_b32_e32 v212, v246
	v_mov_b32_e32 v213, v247
	v_add_u32_e32 v246, 0x80, v240
	v_ashrrev_i32_e32 v247, 31, v246
	v_lshlrev_b64 v[246:247], 10, v[246:247]
	v_lshl_add_u64 v[246:247], s[8:9], 0, v[246:247]
	v_lshl_add_u64 v[250:251], v[246:247], 0, v[248:249]
	v_mov_b32_e32 v214, v250
	v_mov_b32_e32 v215, v251
	v_lshl_add_u64 v[246:247], v[246:247], 0, v[242:243]
	v_mov_b32_e32 v216, v246
	v_mov_b32_e32 v217, v247
	v_add_u32_e32 v246, 0x90, v240
	v_ashrrev_i32_e32 v247, 31, v246
	v_lshlrev_b64 v[246:247], 10, v[246:247]
	v_lshl_add_u64 v[246:247], s[8:9], 0, v[246:247]
	v_lshl_add_u64 v[250:251], v[246:247], 0, v[248:249]
	v_mov_b32_e32 v218, v250
	v_mov_b32_e32 v219, v251
	v_lshl_add_u64 v[246:247], v[246:247], 0, v[242:243]
	v_mov_b32_e32 v220, v246
	v_mov_b32_e32 v221, v247
	v_add_u32_e32 v246, 0xa0, v240
	v_ashrrev_i32_e32 v247, 31, v246
	v_lshlrev_b64 v[246:247], 10, v[246:247]
	v_lshl_add_u64 v[246:247], s[8:9], 0, v[246:247]
	v_lshl_add_u64 v[250:251], v[246:247], 0, v[248:249]
	v_mov_b32_e32 v222, v250
	v_mov_b32_e32 v223, v251
	v_lshl_add_u64 v[246:247], v[246:247], 0, v[242:243]
	v_mov_b32_e32 v226, v246
	v_mov_b32_e32 v227, v247
	v_add_u32_e32 v240, 0xb0, v240
	v_ashrrev_i32_e32 v241, 31, v240
	v_lshlrev_b64 v[240:241], 10, v[240:241]
	v_lshl_add_u64 v[240:241], s[8:9], 0, v[240:241]
	v_lshl_add_u64 v[246:247], v[240:241], 0, v[248:249]
	v_mov_b32_e32 v232, v246
	v_mov_b32_e32 v233, v247
	v_lshl_add_u64 v[240:241], v[240:241], 0, v[242:243]
	v_mov_b32_e32 v162, v240
	v_mov_b32_e32 v163, v241
	v_mov_b32_e32 v142, v1
	v_mov_b32_e32 v143, v148
	v_lshl_add_u32 v146, v143, 3, s0
	v_ashrrev_i32_e32 v147, 31, v146
	v_add_u32_e32 v144, s1, v142
	v_lshl_add_u64 v[142:143], v[146:147], 2, s[12:13]
	global_load_dwordx4 v[164:167], v[196:197], off offset:16
	global_load_dwordx4 v[168:171], v[196:197], off
	global_load_dwordx4 v[172:175], v[198:199], off
	global_load_dwordx4 v[176:179], v[196:197], off offset:528
	global_load_dwordx4 v[180:183], v[196:197], off offset:512
	s_waitcnt vmcnt(4)
	global_load_dwordx4 v[184:187], v[200:201], off
	s_waitcnt vmcnt(4)
	v_ashrrev_i32_e32 v145, 31, v144
	v_lshlrev_b64 v[160:161], 10, v[144:145]
	s_movk_i32 s19, 0xc00
	s_mov_b64 s[38:39], -1
	s_andn2_b64 vcc, exec, s[4:5]
	v_pk_add_f32 v[124:125], v[124:125], v[166:167]
	v_pk_add_f32 v[128:129], v[128:129], v[170:171]
	v_pk_add_f32 v[156:157], v[126:127], v[168:169]
	v_pk_add_f32 v[158:159], v[122:123], v[164:165]
	v_lshl_add_u64 v[126:127], s[8:9], 0, v[160:161]
	v_lshlrev_b64 v[122:123], 1, v[146:147]
	v_lshl_add_u64 v[152:153], v[126:127], 0, v[122:123]
	global_load_dwordx4 v[188:191], v[196:197], off offset:16
	s_waitcnt vmcnt(4)
	v_mul_f32_e32 v145, 0xbfb8aa3b, v156
	v_exp_f32_e32 v145, v145
	v_mul_f32_e32 v128, 0xbfb8aa3b, v128
	v_mul_f32_e32 v129, 0xbfb8aa3b, v129
	v_exp_f32_e32 v128, v128
	v_add_f32_e32 v145, 1.0, v145
	v_rcp_f32_e32 v156, v145
	v_mul_f32_e32 v145, 0xbfb8aa3b, v158
	v_exp_f32_e32 v145, v145
	v_mul_f32_e32 v124, 0xbfb8aa3b, v124
	v_exp_f32_e32 v129, v129
	v_mul_f32_e32 v125, 0xbfb8aa3b, v125
	v_add_f32_e32 v145, 1.0, v145
	v_rcp_f32_e32 v158, v145
	v_mul_f32_e32 v145, 0xbfb8aa3b, v157
	v_exp_f32_e32 v145, v145
	v_exp_f32_e32 v124, v124
	v_exp_f32_e32 v125, v125
	v_add_f32_e32 v128, 1.0, v128
	v_add_f32_e32 v145, 1.0, v145
	v_rcp_f32_e32 v157, v145
	v_mul_f32_e32 v145, 0xbfb8aa3b, v159
	v_exp_f32_e32 v145, v145
	v_add_f32_e32 v129, 1.0, v129
	v_rcp_f32_e32 v128, v128
	v_add_f32_e32 v124, 1.0, v124
	v_rcp_f32_e32 v129, v129
	v_add_f32_e32 v125, 1.0, v125
	v_rcp_f32_e32 v124, v124
	v_rcp_f32_e32 v125, v125
	v_add_f32_e32 v145, 1.0, v145
	v_rcp_f32_e32 v159, v145
	v_add_u32_e32 v146, 0x80, v146
	v_ashrrev_i32_e32 v147, 31, v146
	v_lshlrev_b32_e32 v160, 16, v172
	v_and_b32_e32 v161, 0xffff0000, v172
	v_lshlrev_b32_e32 v152, 16, v173
	v_and_b32_e32 v153, 0xffff0000, v173
	v_pk_mul_f32 v[128:129], v[128:129], v[152:153]
	v_lshlrev_b32_e32 v152, 16, v175
	v_and_b32_e32 v153, 0xffff0000, v175
	v_pk_mul_f32 v[124:125], v[124:125], v[152:153]
	v_pk_mul_f32 v[156:157], v[156:157], v[160:161]
	v_lshlrev_b32_e32 v160, 16, v174
	v_and_b32_e32 v161, 0xffff0000, v174
	v_cvt_pk_bf16_f32 v155, v124, v125
	v_mov_b64_e32 v[124:125], s[14:15]
	v_pk_mul_f32 v[158:159], v[158:159], v[160:161]
	v_cvt_pk_bf16_f32 v153, v128, v129
	v_mad_i64_i32 v[128:129], s[0:1], v144, s19, v[124:125]
	v_cvt_pk_bf16_f32 v152, v156, v157
	v_cvt_pk_bf16_f32 v154, v158, v159
	v_lshl_add_u64 v[128:129], v[128:129], 0, v[122:123]
	global_store_dwordx4 v[128:129], v[152:155], off
	global_load_dwordx4 v[192:195], v[196:197], off
	s_waitcnt vmcnt(5)
	s_nop 0
	global_load_dwordx4 v[164:167], v[202:203], off
	s_waitcnt vmcnt(5)
	v_pk_add_f32 v[152:153], v[114:115], v[176:177]
	v_lshlrev_b64 v[114:115], 1, v[146:147]
	v_pk_add_f32 v[154:155], v[116:117], v[178:179]
	v_lshl_add_u64 v[116:117], v[126:127], 0, v[114:115]
	v_pk_add_f32 v[156:157], v[118:119], v[180:181]
	global_load_dwordx4 v[168:171], v[196:197], off offset:528
	s_waitcnt vmcnt(5)
	v_mul_f32_e32 v127, 0xbfb8aa3b, v152
	v_exp_f32_e32 v127, v127
	v_mul_f32_e32 v126, 0xbfb8aa3b, v156
	v_pk_add_f32 v[120:121], v[120:121], v[182:183]
	v_exp_f32_e32 v126, v126
	v_add_f32_e32 v127, 1.0, v127
	v_rcp_f32_e32 v146, v127
	v_mul_f32_e32 v127, 0xbfb8aa3b, v157
	v_exp_f32_e32 v127, v127
	v_add_f32_e32 v126, 1.0, v126
	v_rcp_f32_e32 v126, v126
	v_add_f32_e32 v127, 1.0, v127
	v_rcp_f32_e32 v127, v127
	v_lshlrev_b32_e32 v156, 16, v184
	v_and_b32_e32 v157, 0xffff0000, v184
	v_mul_f32_e32 v116, 0xbfb8aa3b, v153
	v_exp_f32_e32 v116, v116
	v_lshlrev_b32_e32 v152, 16, v186
	v_and_b32_e32 v153, 0xffff0000, v186
	v_mul_f32_e32 v118, 0xbfb8aa3b, v121
	v_add_f32_e32 v116, 1.0, v116
	v_rcp_f32_e32 v147, v116
	v_mul_f32_e32 v116, 0xbfb8aa3b, v120
	v_exp_f32_e32 v116, v116
	v_exp_f32_e32 v118, v118
	v_pk_mul_f32 v[146:147], v[146:147], v[152:153]
	v_lshlrev_b32_e32 v152, 16, v185
	v_add_f32_e32 v116, 1.0, v116
	v_rcp_f32_e32 v120, v116
	v_mul_f32_e32 v116, 0xbfb8aa3b, v154
	v_and_b32_e32 v153, 0xffff0000, v185
	v_mul_f32_e32 v117, 0xbfb8aa3b, v155
	v_exp_f32_e32 v116, v116
	v_exp_f32_e32 v117, v117
	v_add_f32_e32 v118, 1.0, v118
	v_rcp_f32_e32 v121, v118
	v_add_f32_e32 v116, 1.0, v116
	v_add_f32_e32 v117, 1.0, v117
	v_rcp_f32_e32 v116, v116
	v_rcp_f32_e32 v117, v117
	v_lshlrev_b32_e32 v118, 16, v187
	v_and_b32_e32 v119, 0xffff0000, v187
	v_pk_mul_f32 v[126:127], v[126:127], v[156:157]
	v_pk_mul_f32 v[120:121], v[120:121], v[152:153]
	v_pk_mul_f32 v[152:153], v[116:117], v[118:119]
	v_cvt_pk_bf16_f32 v116, v126, v127
	v_cvt_pk_bf16_f32 v117, v120, v121
	v_cvt_pk_bf16_f32 v118, v146, v147
	v_cvt_pk_bf16_f32 v119, v152, v153
	global_store_dwordx4 v[128:129], v[116:119], off offset:256
	global_load_dwordx4 v[172:175], v[196:197], off offset:512
	s_waitcnt vmcnt(6)
	s_nop 0
	global_load_dwordx4 v[176:179], v[204:205], off
	s_waitcnt vmcnt(5)
	v_add_u32_e32 v116, 16, v144
	v_ashrrev_i32_e32 v117, 31, v116
	v_lshlrev_b64 v[146:147], 10, v[116:117]
	v_pk_add_f32 v[118:119], v[106:107], v[188:189]
	v_pk_add_f32 v[126:127], v[110:111], v[192:193]
	v_lshl_add_u64 v[110:111], s[8:9], 0, v[146:147]
	v_lshl_add_u64 v[106:107], v[110:111], 0, v[122:123]
	v_pk_add_f32 v[120:121], v[108:109], v[190:191]
	global_load_dwordx4 v[180:183], v[196:197], off offset:16
	s_waitcnt vmcnt(5)
	v_mul_f32_e32 v117, 0xbfb8aa3b, v126
	v_exp_f32_e32 v117, v117
	v_pk_add_f32 v[112:113], v[112:113], v[194:195]
	v_add_f32_e32 v117, 1.0, v117
	v_rcp_f32_e32 v126, v117
	v_mul_f32_e32 v117, 0xbfb8aa3b, v118
	v_exp_f32_e32 v117, v117
	v_lshlrev_b32_e32 v128, 16, v164
	v_add_f32_e32 v117, 1.0, v117
	v_and_b32_e32 v129, 0xffff0000, v164
	v_mul_f32_e32 v106, 0xbfb8aa3b, v119
	v_rcp_f32_e32 v118, v117
	v_mul_f32_e32 v117, 0xbfb8aa3b, v127
	v_exp_f32_e32 v106, v106
	v_exp_f32_e32 v117, v117
	v_add_f32_e32 v106, 1.0, v106
	v_add_f32_e32 v117, 1.0, v117
	v_rcp_f32_e32 v119, v106
	v_mul_f32_e32 v106, 0xbfb8aa3b, v112
	v_rcp_f32_e32 v127, v117
	v_exp_f32_e32 v106, v106
	v_pk_mul_f32 v[126:127], v[126:127], v[128:129]
	v_lshlrev_b32_e32 v128, 16, v166
	v_and_b32_e32 v129, 0xffff0000, v166
	v_add_f32_e32 v106, 1.0, v106
	v_mul_f32_e32 v108, 0xbfb8aa3b, v113
	v_pk_mul_f32 v[118:119], v[118:119], v[128:129]
	v_rcp_f32_e32 v112, v106
	v_mul_f32_e32 v106, 0xbfb8aa3b, v120
	v_exp_f32_e32 v108, v108
	v_lshlrev_b32_e32 v128, 16, v165
	v_and_b32_e32 v129, 0xffff0000, v165
	v_mul_f32_e32 v107, 0xbfb8aa3b, v121
	v_exp_f32_e32 v106, v106
	v_exp_f32_e32 v107, v107
	v_add_f32_e32 v108, 1.0, v108
	v_rcp_f32_e32 v113, v108
	v_add_f32_e32 v106, 1.0, v106
	v_add_f32_e32 v107, 1.0, v107
	v_rcp_f32_e32 v106, v106
	v_rcp_f32_e32 v107, v107
	v_pk_mul_f32 v[112:113], v[112:113], v[128:129]
	v_lshlrev_b32_e32 v108, 16, v167
	v_and_b32_e32 v109, 0xffff0000, v167
	v_pk_mul_f32 v[120:121], v[106:107], v[108:109]
	v_cvt_pk_bf16_f32 v107, v112, v113
	v_mad_i64_i32 v[112:113], s[0:1], v116, s19, v[124:125]
	v_cvt_pk_bf16_f32 v106, v126, v127
	v_cvt_pk_bf16_f32 v108, v118, v119
	v_cvt_pk_bf16_f32 v109, v120, v121
	v_lshl_add_u64 v[112:113], v[112:113], 0, v[122:123]
	global_store_dwordx4 v[112:113], v[106:109], off
	global_load_dwordx4 v[184:187], v[196:197], off
	s_waitcnt vmcnt(6)
	s_nop 0
	global_load_dwordx4 v[188:191], v[206:207], off
	s_waitcnt vmcnt(5)
	v_pk_add_f32 v[106:107], v[98:99], v[168:169]
	v_lshl_add_u64 v[98:99], v[110:111], 0, v[114:115]
	v_pk_add_f32 v[108:109], v[100:101], v[170:171]
	global_load_dwordx4 v[192:195], v[196:197], off offset:528
	s_waitcnt vmcnt(5)
	v_pk_add_f32 v[102:103], v[102:103], v[172:173]
	v_mul_f32_e32 v106, 0xbfb8aa3b, v106
	v_mul_f32_e32 v102, 0xbfb8aa3b, v102
	v_mul_f32_e32 v103, 0xbfb8aa3b, v103
	v_exp_f32_e32 v102, v102
	v_exp_f32_e32 v103, v103
	v_exp_f32_e32 v106, v106
	v_pk_add_f32 v[104:105], v[104:105], v[174:175]
	v_add_f32_e32 v102, 1.0, v102
	v_add_f32_e32 v103, 1.0, v103
	v_rcp_f32_e32 v102, v102
	v_add_f32_e32 v106, 1.0, v106
	v_rcp_f32_e32 v103, v103
	v_rcp_f32_e32 v106, v106
	v_lshlrev_b32_e32 v110, 16, v176
	v_and_b32_e32 v111, 0xffff0000, v176
	v_mul_f32_e32 v98, 0xbfb8aa3b, v107
	v_exp_f32_e32 v98, v98
	v_pk_mul_f32 v[102:103], v[102:103], v[110:111]
	v_lshlrev_b32_e32 v110, 16, v178
	v_and_b32_e32 v111, 0xffff0000, v178
	v_add_f32_e32 v98, 1.0, v98
	v_rcp_f32_e32 v107, v98
	v_mul_f32_e32 v98, 0xbfb8aa3b, v104
	v_exp_f32_e32 v98, v98
	v_mul_f32_e32 v100, 0xbfb8aa3b, v105
	v_pk_mul_f32 v[106:107], v[106:107], v[110:111]
	v_lshlrev_b32_e32 v110, 16, v177
	v_add_f32_e32 v98, 1.0, v98
	v_rcp_f32_e32 v104, v98
	v_mul_f32_e32 v98, 0xbfb8aa3b, v108
	v_and_b32_e32 v111, 0xffff0000, v177
	v_mul_f32_e32 v99, 0xbfb8aa3b, v109
	v_exp_f32_e32 v98, v98
	v_exp_f32_e32 v100, v100
	v_exp_f32_e32 v99, v99
	v_add_f32_e32 v98, 1.0, v98
	v_add_f32_e32 v100, 1.0, v100
	v_add_f32_e32 v99, 1.0, v99
	v_rcp_f32_e32 v98, v98
	v_rcp_f32_e32 v105, v100
	v_rcp_f32_e32 v99, v99
	v_lshlrev_b32_e32 v100, 16, v179
	v_and_b32_e32 v101, 0xffff0000, v179
	v_pk_mul_f32 v[104:105], v[104:105], v[110:111]
	v_pk_mul_f32 v[108:109], v[98:99], v[100:101]
	v_cvt_pk_bf16_f32 v98, v102, v103
	v_cvt_pk_bf16_f32 v99, v104, v105
	v_cvt_pk_bf16_f32 v100, v106, v107
	v_cvt_pk_bf16_f32 v101, v108, v109
	global_store_dwordx4 v[112:113], v[98:101], off offset:256
	global_load_dwordx4 v[164:167], v[196:197], off offset:512
	s_waitcnt vmcnt(6)
	s_nop 0
	global_load_dwordx4 v[168:171], v[208:209], off
	s_waitcnt vmcnt(5)
	v_add_u32_e32 v98, 32, v144
	v_ashrrev_i32_e32 v99, 31, v98
	v_lshlrev_b64 v[108:109], 10, v[98:99]
	v_pk_add_f32 v[100:101], v[90:91], v[180:181]
	v_pk_add_f32 v[104:105], v[94:95], v[184:185]
	v_lshl_add_u64 v[94:95], s[8:9], 0, v[108:109]
	v_lshl_add_u64 v[90:91], v[94:95], 0, v[122:123]
	v_pk_add_f32 v[102:103], v[92:93], v[182:183]
	global_load_dwordx4 v[172:175], v[196:197], off offset:16
	s_waitcnt vmcnt(5)
	v_mul_f32_e32 v99, 0xbfb8aa3b, v104
	v_exp_f32_e32 v99, v99
	v_pk_add_f32 v[96:97], v[96:97], v[186:187]
	v_add_f32_e32 v99, 1.0, v99
	v_rcp_f32_e32 v104, v99
	v_mul_f32_e32 v99, 0xbfb8aa3b, v100
	v_exp_f32_e32 v99, v99
	v_lshlrev_b32_e32 v106, 16, v188
	v_add_f32_e32 v99, 1.0, v99
	v_and_b32_e32 v107, 0xffff0000, v188
	v_mul_f32_e32 v90, 0xbfb8aa3b, v101
	v_rcp_f32_e32 v100, v99
	v_mul_f32_e32 v99, 0xbfb8aa3b, v105
	v_exp_f32_e32 v90, v90
	v_exp_f32_e32 v99, v99
	v_add_f32_e32 v90, 1.0, v90
	v_add_f32_e32 v99, 1.0, v99
	v_rcp_f32_e32 v101, v90
	v_mul_f32_e32 v90, 0xbfb8aa3b, v96
	v_rcp_f32_e32 v105, v99
	v_exp_f32_e32 v90, v90
	v_pk_mul_f32 v[104:105], v[104:105], v[106:107]
	v_lshlrev_b32_e32 v106, 16, v190
	v_and_b32_e32 v107, 0xffff0000, v190
	v_add_f32_e32 v90, 1.0, v90
	v_mul_f32_e32 v92, 0xbfb8aa3b, v97
	v_pk_mul_f32 v[100:101], v[100:101], v[106:107]
	v_rcp_f32_e32 v96, v90
	v_mul_f32_e32 v90, 0xbfb8aa3b, v102
	v_exp_f32_e32 v92, v92
	v_lshlrev_b32_e32 v106, 16, v189
	v_and_b32_e32 v107, 0xffff0000, v189
	v_mul_f32_e32 v91, 0xbfb8aa3b, v103
	v_exp_f32_e32 v90, v90
	v_exp_f32_e32 v91, v91
	v_add_f32_e32 v92, 1.0, v92
	v_rcp_f32_e32 v97, v92
	v_add_f32_e32 v90, 1.0, v90
	v_add_f32_e32 v91, 1.0, v91
	v_rcp_f32_e32 v90, v90
	v_rcp_f32_e32 v91, v91
	v_pk_mul_f32 v[96:97], v[96:97], v[106:107]
	v_lshlrev_b32_e32 v92, 16, v191
	v_and_b32_e32 v93, 0xffff0000, v191
	v_pk_mul_f32 v[102:103], v[90:91], v[92:93]
	v_cvt_pk_bf16_f32 v91, v96, v97
	v_mad_i64_i32 v[96:97], s[0:1], v98, s19, v[124:125]
	v_cvt_pk_bf16_f32 v90, v104, v105
	v_cvt_pk_bf16_f32 v92, v100, v101
	v_cvt_pk_bf16_f32 v93, v102, v103
	v_lshl_add_u64 v[96:97], v[96:97], 0, v[122:123]
	global_store_dwordx4 v[96:97], v[90:93], off
	global_load_dwordx4 v[176:179], v[196:197], off
	s_waitcnt vmcnt(6)
	s_nop 0
	global_load_dwordx4 v[180:183], v[210:211], off
	s_waitcnt vmcnt(5)
	v_pk_add_f32 v[90:91], v[82:83], v[192:193]
	v_lshl_add_u64 v[82:83], v[94:95], 0, v[114:115]
	v_pk_add_f32 v[92:93], v[84:85], v[194:195]
	global_load_dwordx4 v[184:187], v[196:197], off offset:528
	s_waitcnt vmcnt(5)
	v_pk_add_f32 v[86:87], v[86:87], v[164:165]
	v_mul_f32_e32 v90, 0xbfb8aa3b, v90
	v_mul_f32_e32 v86, 0xbfb8aa3b, v86
	v_mul_f32_e32 v87, 0xbfb8aa3b, v87
	v_exp_f32_e32 v86, v86
	v_exp_f32_e32 v87, v87
	v_exp_f32_e32 v90, v90
	v_pk_add_f32 v[88:89], v[88:89], v[166:167]
	v_add_f32_e32 v86, 1.0, v86
	v_add_f32_e32 v87, 1.0, v87
	v_rcp_f32_e32 v86, v86
	v_add_f32_e32 v90, 1.0, v90
	v_rcp_f32_e32 v87, v87
	v_rcp_f32_e32 v90, v90
	v_lshlrev_b32_e32 v94, 16, v168
	v_and_b32_e32 v95, 0xffff0000, v168
	v_mul_f32_e32 v82, 0xbfb8aa3b, v91
	v_exp_f32_e32 v82, v82
	v_pk_mul_f32 v[86:87], v[86:87], v[94:95]
	v_lshlrev_b32_e32 v94, 16, v170
	v_and_b32_e32 v95, 0xffff0000, v170
	v_add_f32_e32 v82, 1.0, v82
	v_rcp_f32_e32 v91, v82
	v_mul_f32_e32 v82, 0xbfb8aa3b, v88
	v_exp_f32_e32 v82, v82
	v_mul_f32_e32 v84, 0xbfb8aa3b, v89
	v_pk_mul_f32 v[90:91], v[90:91], v[94:95]
	v_lshlrev_b32_e32 v94, 16, v169
	v_add_f32_e32 v82, 1.0, v82
	v_rcp_f32_e32 v88, v82
	v_mul_f32_e32 v82, 0xbfb8aa3b, v92
	v_and_b32_e32 v95, 0xffff0000, v169
	v_mul_f32_e32 v83, 0xbfb8aa3b, v93
	v_exp_f32_e32 v82, v82
	v_exp_f32_e32 v84, v84
	v_exp_f32_e32 v83, v83
	v_add_f32_e32 v82, 1.0, v82
	v_add_f32_e32 v84, 1.0, v84
	v_add_f32_e32 v83, 1.0, v83
	v_rcp_f32_e32 v82, v82
	v_rcp_f32_e32 v89, v84
	v_rcp_f32_e32 v83, v83
	v_lshlrev_b32_e32 v84, 16, v171
	v_and_b32_e32 v85, 0xffff0000, v171
	v_pk_mul_f32 v[88:89], v[88:89], v[94:95]
	v_pk_mul_f32 v[92:93], v[82:83], v[84:85]
	v_cvt_pk_bf16_f32 v82, v86, v87
	v_cvt_pk_bf16_f32 v83, v88, v89
	v_cvt_pk_bf16_f32 v84, v90, v91
	v_cvt_pk_bf16_f32 v85, v92, v93
	global_store_dwordx4 v[96:97], v[82:85], off offset:256
	global_load_dwordx4 v[188:191], v[196:197], off offset:512
	s_waitcnt vmcnt(6)
	s_nop 0
	global_load_dwordx4 v[192:195], v[212:213], off
	s_waitcnt vmcnt(5)
	v_add_u32_e32 v82, 48, v144
	v_ashrrev_i32_e32 v83, 31, v82
	v_lshlrev_b64 v[92:93], 10, v[82:83]
	v_pk_add_f32 v[84:85], v[74:75], v[172:173]
	v_pk_add_f32 v[88:89], v[78:79], v[176:177]
	v_lshl_add_u64 v[78:79], s[8:9], 0, v[92:93]
	v_lshl_add_u64 v[74:75], v[78:79], 0, v[122:123]
	v_pk_add_f32 v[86:87], v[76:77], v[174:175]
	global_load_dwordx4 v[164:167], v[196:197], off offset:16
	s_waitcnt vmcnt(5)
	v_mul_f32_e32 v83, 0xbfb8aa3b, v88
	v_exp_f32_e32 v83, v83
	v_pk_add_f32 v[80:81], v[80:81], v[178:179]
	v_add_f32_e32 v83, 1.0, v83
	v_rcp_f32_e32 v88, v83
	v_mul_f32_e32 v83, 0xbfb8aa3b, v84
	v_exp_f32_e32 v83, v83
	v_lshlrev_b32_e32 v90, 16, v180
	v_add_f32_e32 v83, 1.0, v83
	v_and_b32_e32 v91, 0xffff0000, v180
	v_mul_f32_e32 v74, 0xbfb8aa3b, v85
	v_rcp_f32_e32 v84, v83
	v_mul_f32_e32 v83, 0xbfb8aa3b, v89
	v_exp_f32_e32 v74, v74
	v_exp_f32_e32 v83, v83
	v_add_f32_e32 v74, 1.0, v74
	v_add_f32_e32 v83, 1.0, v83
	v_rcp_f32_e32 v85, v74
	v_mul_f32_e32 v74, 0xbfb8aa3b, v80
	v_rcp_f32_e32 v89, v83
	v_exp_f32_e32 v74, v74
	v_pk_mul_f32 v[88:89], v[88:89], v[90:91]
	v_lshlrev_b32_e32 v90, 16, v182
	v_and_b32_e32 v91, 0xffff0000, v182
	v_add_f32_e32 v74, 1.0, v74
	v_mul_f32_e32 v76, 0xbfb8aa3b, v81
	v_pk_mul_f32 v[84:85], v[84:85], v[90:91]
	v_rcp_f32_e32 v80, v74
	v_mul_f32_e32 v74, 0xbfb8aa3b, v86
	v_exp_f32_e32 v76, v76
	v_lshlrev_b32_e32 v90, 16, v181
	v_and_b32_e32 v91, 0xffff0000, v181
	v_mul_f32_e32 v75, 0xbfb8aa3b, v87
	v_exp_f32_e32 v74, v74
	v_exp_f32_e32 v75, v75
	v_add_f32_e32 v76, 1.0, v76
	v_rcp_f32_e32 v81, v76
	v_add_f32_e32 v74, 1.0, v74
	v_add_f32_e32 v75, 1.0, v75
	v_rcp_f32_e32 v74, v74
	v_rcp_f32_e32 v75, v75
	v_pk_mul_f32 v[80:81], v[80:81], v[90:91]
	v_lshlrev_b32_e32 v76, 16, v183
	v_and_b32_e32 v77, 0xffff0000, v183
	v_pk_mul_f32 v[86:87], v[74:75], v[76:77]
	v_cvt_pk_bf16_f32 v75, v80, v81
	v_mad_i64_i32 v[80:81], s[0:1], v82, s19, v[124:125]
	v_cvt_pk_bf16_f32 v74, v88, v89
	v_cvt_pk_bf16_f32 v76, v84, v85
	v_cvt_pk_bf16_f32 v77, v86, v87
	v_lshl_add_u64 v[80:81], v[80:81], 0, v[122:123]
	global_store_dwordx4 v[80:81], v[74:77], off
	global_load_dwordx4 v[168:171], v[196:197], off
	s_waitcnt vmcnt(6)
	s_nop 0
	global_load_dwordx4 v[172:175], v[214:215], off
	s_waitcnt vmcnt(5)
	v_pk_add_f32 v[74:75], v[66:67], v[184:185]
	v_lshl_add_u64 v[66:67], v[78:79], 0, v[114:115]
	v_pk_add_f32 v[76:77], v[68:69], v[186:187]
	global_load_dwordx4 v[176:179], v[196:197], off offset:528
	s_waitcnt vmcnt(5)
	v_pk_add_f32 v[70:71], v[70:71], v[188:189]
	v_mul_f32_e32 v74, 0xbfb8aa3b, v74
	v_mul_f32_e32 v70, 0xbfb8aa3b, v70
	v_mul_f32_e32 v71, 0xbfb8aa3b, v71
	v_exp_f32_e32 v70, v70
	v_exp_f32_e32 v71, v71
	v_exp_f32_e32 v74, v74
	v_pk_add_f32 v[72:73], v[72:73], v[190:191]
	v_add_f32_e32 v70, 1.0, v70
	v_add_f32_e32 v71, 1.0, v71
	v_rcp_f32_e32 v70, v70
	v_add_f32_e32 v74, 1.0, v74
	v_rcp_f32_e32 v71, v71
	v_rcp_f32_e32 v74, v74
	v_lshlrev_b32_e32 v78, 16, v192
	v_and_b32_e32 v79, 0xffff0000, v192
	v_mul_f32_e32 v66, 0xbfb8aa3b, v75
	v_exp_f32_e32 v66, v66
	v_pk_mul_f32 v[70:71], v[70:71], v[78:79]
	v_lshlrev_b32_e32 v78, 16, v194
	v_and_b32_e32 v79, 0xffff0000, v194
	v_add_f32_e32 v66, 1.0, v66
	v_rcp_f32_e32 v75, v66
	v_mul_f32_e32 v66, 0xbfb8aa3b, v72
	v_exp_f32_e32 v66, v66
	v_mul_f32_e32 v68, 0xbfb8aa3b, v73
	v_pk_mul_f32 v[74:75], v[74:75], v[78:79]
	v_lshlrev_b32_e32 v78, 16, v193
	v_add_f32_e32 v66, 1.0, v66
	v_rcp_f32_e32 v72, v66
	v_mul_f32_e32 v66, 0xbfb8aa3b, v76
	v_and_b32_e32 v79, 0xffff0000, v193
	v_mul_f32_e32 v67, 0xbfb8aa3b, v77
	v_exp_f32_e32 v66, v66
	v_exp_f32_e32 v68, v68
	v_exp_f32_e32 v67, v67
	v_add_f32_e32 v66, 1.0, v66
	v_add_f32_e32 v68, 1.0, v68
	v_add_f32_e32 v67, 1.0, v67
	v_rcp_f32_e32 v66, v66
	v_rcp_f32_e32 v73, v68
	v_rcp_f32_e32 v67, v67
	v_lshlrev_b32_e32 v68, 16, v195
	v_and_b32_e32 v69, 0xffff0000, v195
	v_pk_mul_f32 v[72:73], v[72:73], v[78:79]
	v_pk_mul_f32 v[76:77], v[66:67], v[68:69]
	v_cvt_pk_bf16_f32 v66, v70, v71
	v_cvt_pk_bf16_f32 v67, v72, v73
	v_cvt_pk_bf16_f32 v68, v74, v75
	v_cvt_pk_bf16_f32 v69, v76, v77
	global_store_dwordx4 v[80:81], v[66:69], off offset:256
	global_load_dwordx4 v[180:183], v[196:197], off offset:512
	s_waitcnt vmcnt(6)
	global_load_dwordx4 v[184:187], v[216:217], off
	s_waitcnt vmcnt(5)
	v_add_u32_e32 v66, 0x80, v144
	v_ashrrev_i32_e32 v67, 31, v66
	v_lshlrev_b64 v[68:69], 10, v[66:67]
	v_pk_add_f32 v[70:71], v[58:59], v[164:165]
	v_pk_add_f32 v[74:75], v[62:63], v[168:169]
	v_lshl_add_u64 v[62:63], s[8:9], 0, v[68:69]
	v_lshl_add_u64 v[58:59], v[62:63], 0, v[122:123]
	v_pk_add_f32 v[72:73], v[60:61], v[166:167]
	global_load_dwordx4 v[188:191], v[196:197], off offset:16
	s_waitcnt vmcnt(5)
	v_mul_f32_e32 v67, 0xbfb8aa3b, v74
	v_exp_f32_e32 v67, v67
	v_pk_add_f32 v[64:65], v[64:65], v[170:171]
	v_add_f32_e32 v67, 1.0, v67
	v_rcp_f32_e32 v68, v67
	v_mul_f32_e32 v67, 0xbfb8aa3b, v70
	v_exp_f32_e32 v67, v67
	v_lshlrev_b32_e32 v74, 16, v172
	v_add_f32_e32 v67, 1.0, v67
	v_rcp_f32_e32 v70, v67
	v_mul_f32_e32 v67, 0xbfb8aa3b, v75
	v_and_b32_e32 v75, 0xffff0000, v172
	v_mul_f32_e32 v58, 0xbfb8aa3b, v71
	v_exp_f32_e32 v58, v58
	v_exp_f32_e32 v67, v67
	v_add_f32_e32 v58, 1.0, v58
	v_add_f32_e32 v67, 1.0, v67
	v_rcp_f32_e32 v71, v58
	v_mul_f32_e32 v58, 0xbfb8aa3b, v64
	v_rcp_f32_e32 v69, v67
	v_exp_f32_e32 v58, v58
	v_pk_mul_f32 v[68:69], v[68:69], v[74:75]
	v_lshlrev_b32_e32 v74, 16, v174
	v_and_b32_e32 v75, 0xffff0000, v174
	v_add_f32_e32 v58, 1.0, v58
	v_mul_f32_e32 v60, 0xbfb8aa3b, v65
	v_pk_mul_f32 v[70:71], v[70:71], v[74:75]
	v_rcp_f32_e32 v64, v58
	v_mul_f32_e32 v58, 0xbfb8aa3b, v72
	v_exp_f32_e32 v60, v60
	v_lshlrev_b32_e32 v74, 16, v173
	v_and_b32_e32 v75, 0xffff0000, v173
	v_mul_f32_e32 v59, 0xbfb8aa3b, v73
	v_exp_f32_e32 v58, v58
	v_exp_f32_e32 v59, v59
	v_add_f32_e32 v60, 1.0, v60
	v_rcp_f32_e32 v65, v60
	v_add_f32_e32 v58, 1.0, v58
	v_add_f32_e32 v59, 1.0, v59
	v_rcp_f32_e32 v58, v58
	v_rcp_f32_e32 v59, v59
	v_pk_mul_f32 v[64:65], v[64:65], v[74:75]
	v_lshlrev_b32_e32 v60, 16, v175
	v_and_b32_e32 v61, 0xffff0000, v175
	v_pk_mul_f32 v[72:73], v[58:59], v[60:61]
	v_cvt_pk_bf16_f32 v59, v64, v65
	v_mad_i64_i32 v[64:65], s[0:1], v66, s19, v[124:125]
	v_cvt_pk_bf16_f32 v58, v68, v69
	v_cvt_pk_bf16_f32 v60, v70, v71
	v_cvt_pk_bf16_f32 v61, v72, v73
	v_lshl_add_u64 v[64:65], v[64:65], 0, v[122:123]
	global_store_dwordx4 v[64:65], v[58:61], off
	global_load_dwordx4 v[192:195], v[196:197], off
	s_waitcnt vmcnt(6)
	s_nop 0
	global_load_dwordx4 v[164:167], v[218:219], off
	s_waitcnt vmcnt(5)
	v_pk_add_f32 v[58:59], v[50:51], v[176:177]
	v_lshl_add_u64 v[50:51], v[62:63], 0, v[114:115]
	v_pk_add_f32 v[60:61], v[52:53], v[178:179]
	global_load_dwordx4 v[168:171], v[196:197], off offset:528
	s_waitcnt vmcnt(5)
	v_pk_add_f32 v[54:55], v[54:55], v[180:181]
	v_mul_f32_e32 v58, 0xbfb8aa3b, v58
	v_mul_f32_e32 v54, 0xbfb8aa3b, v54
	v_mul_f32_e32 v55, 0xbfb8aa3b, v55
	v_exp_f32_e32 v54, v54
	v_exp_f32_e32 v55, v55
	v_exp_f32_e32 v58, v58
	v_pk_add_f32 v[56:57], v[56:57], v[182:183]
	v_add_f32_e32 v54, 1.0, v54
	v_add_f32_e32 v55, 1.0, v55
	v_rcp_f32_e32 v54, v54
	v_add_f32_e32 v58, 1.0, v58
	v_rcp_f32_e32 v55, v55
	v_rcp_f32_e32 v58, v58
	v_lshlrev_b32_e32 v62, 16, v184
	v_and_b32_e32 v63, 0xffff0000, v184
	v_mul_f32_e32 v50, 0xbfb8aa3b, v59
	v_exp_f32_e32 v50, v50
	v_pk_mul_f32 v[54:55], v[54:55], v[62:63]
	v_lshlrev_b32_e32 v62, 16, v186
	v_and_b32_e32 v63, 0xffff0000, v186
	v_add_f32_e32 v50, 1.0, v50
	v_rcp_f32_e32 v59, v50
	v_mul_f32_e32 v50, 0xbfb8aa3b, v56
	v_exp_f32_e32 v50, v50
	v_mul_f32_e32 v52, 0xbfb8aa3b, v57
	v_pk_mul_f32 v[58:59], v[58:59], v[62:63]
	v_lshlrev_b32_e32 v62, 16, v185
	v_add_f32_e32 v50, 1.0, v50
	v_rcp_f32_e32 v56, v50
	v_mul_f32_e32 v50, 0xbfb8aa3b, v60
	v_and_b32_e32 v63, 0xffff0000, v185
	v_mul_f32_e32 v51, 0xbfb8aa3b, v61
	v_exp_f32_e32 v50, v50
	v_exp_f32_e32 v52, v52
	v_exp_f32_e32 v51, v51
	v_add_f32_e32 v50, 1.0, v50
	v_add_f32_e32 v52, 1.0, v52
	v_add_f32_e32 v51, 1.0, v51
	v_rcp_f32_e32 v50, v50
	v_rcp_f32_e32 v57, v52
	v_rcp_f32_e32 v51, v51
	v_lshlrev_b32_e32 v52, 16, v187
	v_and_b32_e32 v53, 0xffff0000, v187
	v_pk_mul_f32 v[56:57], v[56:57], v[62:63]
	v_pk_mul_f32 v[60:61], v[50:51], v[52:53]
	v_cvt_pk_bf16_f32 v50, v54, v55
	v_cvt_pk_bf16_f32 v51, v56, v57
	v_cvt_pk_bf16_f32 v52, v58, v59
	v_cvt_pk_bf16_f32 v53, v60, v61
	global_store_dwordx4 v[64:65], v[50:53], off offset:256
	global_load_dwordx4 v[172:175], v[196:197], off offset:512
	s_waitcnt vmcnt(6)
	s_nop 0
	global_load_dwordx4 v[176:179], v[220:221], off
	s_waitcnt vmcnt(5)
	v_add_u32_e32 v50, 0x90, v144
	v_ashrrev_i32_e32 v51, 31, v50
	v_lshlrev_b64 v[60:61], 10, v[50:51]
	v_pk_add_f32 v[52:53], v[42:43], v[188:189]
	v_pk_add_f32 v[56:57], v[46:47], v[192:193]
	v_lshl_add_u64 v[46:47], s[8:9], 0, v[60:61]
	v_lshl_add_u64 v[42:43], v[46:47], 0, v[122:123]
	v_pk_add_f32 v[54:55], v[44:45], v[190:191]
	global_load_dwordx4 v[180:183], v[196:197], off offset:16
	s_waitcnt vmcnt(5)
	v_mul_f32_e32 v51, 0xbfb8aa3b, v56
	v_exp_f32_e32 v51, v51
	v_pk_add_f32 v[48:49], v[48:49], v[194:195]
	v_add_f32_e32 v51, 1.0, v51
	v_rcp_f32_e32 v56, v51
	v_mul_f32_e32 v51, 0xbfb8aa3b, v52
	v_exp_f32_e32 v51, v51
	v_lshlrev_b32_e32 v58, 16, v164
	v_add_f32_e32 v51, 1.0, v51
	v_and_b32_e32 v59, 0xffff0000, v164
	v_mul_f32_e32 v42, 0xbfb8aa3b, v53
	v_rcp_f32_e32 v52, v51
	v_mul_f32_e32 v51, 0xbfb8aa3b, v57
	v_exp_f32_e32 v42, v42
	v_exp_f32_e32 v51, v51
	v_add_f32_e32 v42, 1.0, v42
	v_add_f32_e32 v51, 1.0, v51
	v_rcp_f32_e32 v53, v42
	v_mul_f32_e32 v42, 0xbfb8aa3b, v48
	v_rcp_f32_e32 v57, v51
	v_exp_f32_e32 v42, v42
	v_pk_mul_f32 v[56:57], v[56:57], v[58:59]
	v_lshlrev_b32_e32 v58, 16, v166
	v_and_b32_e32 v59, 0xffff0000, v166
	v_add_f32_e32 v42, 1.0, v42
	v_mul_f32_e32 v44, 0xbfb8aa3b, v49
	v_pk_mul_f32 v[52:53], v[52:53], v[58:59]
	v_rcp_f32_e32 v48, v42
	v_mul_f32_e32 v42, 0xbfb8aa3b, v54
	v_exp_f32_e32 v44, v44
	v_lshlrev_b32_e32 v58, 16, v165
	v_and_b32_e32 v59, 0xffff0000, v165
	v_mul_f32_e32 v43, 0xbfb8aa3b, v55
	v_exp_f32_e32 v42, v42
	v_exp_f32_e32 v43, v43
	v_add_f32_e32 v44, 1.0, v44
	v_rcp_f32_e32 v49, v44
	v_add_f32_e32 v42, 1.0, v42
	v_add_f32_e32 v43, 1.0, v43
	v_rcp_f32_e32 v42, v42
	v_rcp_f32_e32 v43, v43
	v_pk_mul_f32 v[48:49], v[48:49], v[58:59]
	v_lshlrev_b32_e32 v44, 16, v167
	v_and_b32_e32 v45, 0xffff0000, v167
	v_pk_mul_f32 v[54:55], v[42:43], v[44:45]
	v_cvt_pk_bf16_f32 v43, v48, v49
	v_mad_i64_i32 v[48:49], s[0:1], v50, s19, v[124:125]
	v_cvt_pk_bf16_f32 v42, v56, v57
	v_cvt_pk_bf16_f32 v44, v52, v53
	v_cvt_pk_bf16_f32 v45, v54, v55
	v_lshl_add_u64 v[48:49], v[48:49], 0, v[122:123]
	global_store_dwordx4 v[48:49], v[42:45], off
	global_load_dwordx4 v[184:187], v[196:197], off
	s_waitcnt vmcnt(6)
	s_nop 0
	global_load_dwordx4 v[188:191], v[222:223], off
	s_waitcnt vmcnt(5)
	v_pk_add_f32 v[42:43], v[34:35], v[168:169]
	v_lshl_add_u64 v[34:35], v[46:47], 0, v[114:115]
	v_pk_add_f32 v[44:45], v[36:37], v[170:171]
	global_load_dwordx4 v[192:195], v[196:197], off offset:528
	s_waitcnt vmcnt(5)
	v_pk_add_f32 v[38:39], v[38:39], v[172:173]
	v_mul_f32_e32 v42, 0xbfb8aa3b, v42
	v_mul_f32_e32 v38, 0xbfb8aa3b, v38
	v_mul_f32_e32 v39, 0xbfb8aa3b, v39
	v_exp_f32_e32 v38, v38
	v_exp_f32_e32 v39, v39
	v_exp_f32_e32 v42, v42
	v_pk_add_f32 v[40:41], v[40:41], v[174:175]
	v_add_f32_e32 v38, 1.0, v38
	v_add_f32_e32 v39, 1.0, v39
	v_rcp_f32_e32 v38, v38
	v_add_f32_e32 v42, 1.0, v42
	v_rcp_f32_e32 v39, v39
	v_rcp_f32_e32 v42, v42
	v_lshlrev_b32_e32 v46, 16, v176
	v_and_b32_e32 v47, 0xffff0000, v176
	v_mul_f32_e32 v34, 0xbfb8aa3b, v43
	v_exp_f32_e32 v34, v34
	v_pk_mul_f32 v[38:39], v[38:39], v[46:47]
	v_lshlrev_b32_e32 v46, 16, v178
	v_and_b32_e32 v47, 0xffff0000, v178
	v_add_f32_e32 v34, 1.0, v34
	v_rcp_f32_e32 v43, v34
	v_mul_f32_e32 v34, 0xbfb8aa3b, v40
	v_exp_f32_e32 v34, v34
	v_mul_f32_e32 v36, 0xbfb8aa3b, v41
	v_pk_mul_f32 v[42:43], v[42:43], v[46:47]
	v_lshlrev_b32_e32 v46, 16, v177
	v_add_f32_e32 v34, 1.0, v34
	v_rcp_f32_e32 v40, v34
	v_mul_f32_e32 v34, 0xbfb8aa3b, v44
	v_and_b32_e32 v47, 0xffff0000, v177
	v_mul_f32_e32 v35, 0xbfb8aa3b, v45
	v_exp_f32_e32 v34, v34
	v_exp_f32_e32 v36, v36
	v_exp_f32_e32 v35, v35
	v_add_f32_e32 v34, 1.0, v34
	v_add_f32_e32 v36, 1.0, v36
	v_add_f32_e32 v35, 1.0, v35
	v_rcp_f32_e32 v34, v34
	v_rcp_f32_e32 v41, v36
	v_rcp_f32_e32 v35, v35
	v_lshlrev_b32_e32 v36, 16, v179
	v_and_b32_e32 v37, 0xffff0000, v179
	v_pk_mul_f32 v[40:41], v[40:41], v[46:47]
	v_pk_mul_f32 v[44:45], v[34:35], v[36:37]
	v_cvt_pk_bf16_f32 v34, v38, v39
	v_cvt_pk_bf16_f32 v35, v40, v41
	v_cvt_pk_bf16_f32 v36, v42, v43
	v_cvt_pk_bf16_f32 v37, v44, v45
	global_store_dwordx4 v[48:49], v[34:37], off offset:256
	global_load_dwordx4 v[164:167], v[196:197], off offset:512
	s_waitcnt vmcnt(6)
	s_nop 0
	global_load_dwordx4 v[168:171], v[226:227], off
	s_waitcnt vmcnt(5)
	v_add_u32_e32 v34, 0xa0, v144
	v_ashrrev_i32_e32 v35, 31, v34
	v_lshlrev_b64 v[44:45], 10, v[34:35]
	v_pk_add_f32 v[36:37], v[26:27], v[180:181]
	v_pk_add_f32 v[40:41], v[30:31], v[184:185]
	v_lshl_add_u64 v[30:31], s[8:9], 0, v[44:45]
	v_lshl_add_u64 v[26:27], v[30:31], 0, v[122:123]
	v_pk_add_f32 v[38:39], v[28:29], v[182:183]
	global_load_dwordx4 v[172:175], v[196:197], off offset:16
	s_waitcnt vmcnt(5)
	v_mul_f32_e32 v35, 0xbfb8aa3b, v40
	v_exp_f32_e32 v35, v35
	v_pk_add_f32 v[32:33], v[32:33], v[186:187]
	v_add_f32_e32 v35, 1.0, v35
	v_rcp_f32_e32 v40, v35
	v_mul_f32_e32 v35, 0xbfb8aa3b, v36
	v_exp_f32_e32 v35, v35
	v_lshlrev_b32_e32 v42, 16, v188
	v_add_f32_e32 v35, 1.0, v35
	v_and_b32_e32 v43, 0xffff0000, v188
	v_mul_f32_e32 v26, 0xbfb8aa3b, v37
	v_rcp_f32_e32 v36, v35
	v_mul_f32_e32 v35, 0xbfb8aa3b, v41
	v_exp_f32_e32 v26, v26
	v_exp_f32_e32 v35, v35
	v_add_f32_e32 v26, 1.0, v26
	v_add_f32_e32 v35, 1.0, v35
	v_rcp_f32_e32 v37, v26
	v_mul_f32_e32 v26, 0xbfb8aa3b, v32
	v_rcp_f32_e32 v41, v35
	v_exp_f32_e32 v26, v26
	v_pk_mul_f32 v[40:41], v[40:41], v[42:43]
	v_lshlrev_b32_e32 v42, 16, v190
	v_and_b32_e32 v43, 0xffff0000, v190
	v_add_f32_e32 v26, 1.0, v26
	v_mul_f32_e32 v28, 0xbfb8aa3b, v33
	v_pk_mul_f32 v[36:37], v[36:37], v[42:43]
	v_rcp_f32_e32 v32, v26
	v_mul_f32_e32 v26, 0xbfb8aa3b, v38
	v_exp_f32_e32 v28, v28
	v_lshlrev_b32_e32 v42, 16, v189
	v_and_b32_e32 v43, 0xffff0000, v189
	v_mul_f32_e32 v27, 0xbfb8aa3b, v39
	v_exp_f32_e32 v26, v26
	v_exp_f32_e32 v27, v27
	v_add_f32_e32 v28, 1.0, v28
	v_rcp_f32_e32 v33, v28
	v_add_f32_e32 v26, 1.0, v26
	v_add_f32_e32 v27, 1.0, v27
	v_rcp_f32_e32 v26, v26
	v_rcp_f32_e32 v27, v27
	v_pk_mul_f32 v[32:33], v[32:33], v[42:43]
	v_lshlrev_b32_e32 v28, 16, v191
	v_and_b32_e32 v29, 0xffff0000, v191
	v_pk_mul_f32 v[38:39], v[26:27], v[28:29]
	v_cvt_pk_bf16_f32 v27, v32, v33
	v_mad_i64_i32 v[32:33], s[0:1], v34, s19, v[124:125]
	v_cvt_pk_bf16_f32 v26, v40, v41
	v_cvt_pk_bf16_f32 v28, v36, v37
	v_cvt_pk_bf16_f32 v29, v38, v39
	v_lshl_add_u64 v[32:33], v[32:33], 0, v[122:123]
	global_store_dwordx4 v[32:33], v[26:29], off
	global_load_dwordx4 v[176:179], v[196:197], off
	s_waitcnt vmcnt(6)
	s_nop 0
	global_load_dwordx4 v[180:183], v[232:233], off
	s_waitcnt vmcnt(5)
	v_pk_add_f32 v[26:27], v[18:19], v[192:193]
	v_lshl_add_u64 v[18:19], v[30:31], 0, v[114:115]
	v_pk_add_f32 v[28:29], v[20:21], v[194:195]
	global_load_dwordx4 v[184:187], v[196:197], off offset:528
	s_waitcnt vmcnt(5)
	v_pk_add_f32 v[22:23], v[22:23], v[164:165]
	v_mul_f32_e32 v26, 0xbfb8aa3b, v26
	v_mul_f32_e32 v22, 0xbfb8aa3b, v22
	v_mul_f32_e32 v23, 0xbfb8aa3b, v23
	v_exp_f32_e32 v22, v22
	v_exp_f32_e32 v23, v23
	v_exp_f32_e32 v26, v26
	v_pk_add_f32 v[24:25], v[24:25], v[166:167]
	v_add_f32_e32 v22, 1.0, v22
	v_add_f32_e32 v23, 1.0, v23
	v_rcp_f32_e32 v22, v22
	v_add_f32_e32 v26, 1.0, v26
	v_rcp_f32_e32 v23, v23
	v_rcp_f32_e32 v26, v26
	v_lshlrev_b32_e32 v30, 16, v168
	v_and_b32_e32 v31, 0xffff0000, v168
	v_mul_f32_e32 v18, 0xbfb8aa3b, v27
	v_exp_f32_e32 v18, v18
	v_pk_mul_f32 v[22:23], v[22:23], v[30:31]
	v_lshlrev_b32_e32 v30, 16, v170
	v_and_b32_e32 v31, 0xffff0000, v170
	v_add_f32_e32 v18, 1.0, v18
	v_rcp_f32_e32 v27, v18
	v_mul_f32_e32 v18, 0xbfb8aa3b, v24
	v_exp_f32_e32 v18, v18
	v_mul_f32_e32 v20, 0xbfb8aa3b, v25
	v_pk_mul_f32 v[26:27], v[26:27], v[30:31]
	v_lshlrev_b32_e32 v30, 16, v169
	v_add_f32_e32 v18, 1.0, v18
	v_rcp_f32_e32 v24, v18
	v_mul_f32_e32 v18, 0xbfb8aa3b, v28
	v_and_b32_e32 v31, 0xffff0000, v169
	v_mul_f32_e32 v19, 0xbfb8aa3b, v29
	v_exp_f32_e32 v18, v18
	v_exp_f32_e32 v20, v20
	v_exp_f32_e32 v19, v19
	v_add_f32_e32 v18, 1.0, v18
	v_add_f32_e32 v20, 1.0, v20
	v_add_f32_e32 v19, 1.0, v19
	v_rcp_f32_e32 v18, v18
	v_rcp_f32_e32 v25, v20
	v_rcp_f32_e32 v19, v19
	v_lshlrev_b32_e32 v20, 16, v171
	v_and_b32_e32 v21, 0xffff0000, v171
	v_pk_mul_f32 v[24:25], v[24:25], v[30:31]
	v_pk_mul_f32 v[28:29], v[18:19], v[20:21]
	v_cvt_pk_bf16_f32 v18, v22, v23
	v_cvt_pk_bf16_f32 v19, v24, v25
	v_cvt_pk_bf16_f32 v20, v26, v27
	v_cvt_pk_bf16_f32 v21, v28, v29
	global_store_dwordx4 v[32:33], v[18:21], off offset:256
	global_load_dwordx4 v[188:191], v[196:197], off offset:512
	s_waitcnt vmcnt(6)
	s_nop 0
	global_load_dwordx4 v[192:195], v[162:163], off
	s_waitcnt vmcnt(5)
	v_add_u32_e32 v18, 0xb0, v144
	v_ashrrev_i32_e32 v19, 31, v18
	v_lshlrev_b64 v[28:29], 10, v[18:19]
	v_pk_add_f32 v[20:21], v[10:11], v[172:173]
	v_pk_add_f32 v[24:25], v[14:15], v[176:177]
	v_lshl_add_u64 v[14:15], s[8:9], 0, v[28:29]
	v_lshl_add_u64 v[10:11], v[14:15], 0, v[122:123]
	v_pk_add_f32 v[22:23], v[12:13], v[174:175]
	s_waitcnt vmcnt(4)
	v_mul_f32_e32 v19, 0xbfb8aa3b, v24
	v_exp_f32_e32 v19, v19
	v_pk_add_f32 v[16:17], v[16:17], v[178:179]
	v_add_f32_e32 v19, 1.0, v19
	v_rcp_f32_e32 v24, v19
	v_mul_f32_e32 v19, 0xbfb8aa3b, v20
	v_exp_f32_e32 v19, v19
	v_lshlrev_b32_e32 v26, 16, v180
	v_add_f32_e32 v19, 1.0, v19
	v_and_b32_e32 v27, 0xffff0000, v180
	v_mul_f32_e32 v10, 0xbfb8aa3b, v21
	v_rcp_f32_e32 v20, v19
	v_mul_f32_e32 v19, 0xbfb8aa3b, v25
	v_exp_f32_e32 v10, v10
	v_exp_f32_e32 v19, v19
	v_add_f32_e32 v10, 1.0, v10
	v_add_f32_e32 v19, 1.0, v19
	v_rcp_f32_e32 v21, v10
	v_mul_f32_e32 v10, 0xbfb8aa3b, v16
	v_rcp_f32_e32 v25, v19
	v_exp_f32_e32 v10, v10
	v_pk_mul_f32 v[24:25], v[24:25], v[26:27]
	v_lshlrev_b32_e32 v26, 16, v182
	v_and_b32_e32 v27, 0xffff0000, v182
	v_add_f32_e32 v10, 1.0, v10
	v_mul_f32_e32 v12, 0xbfb8aa3b, v17
	v_pk_mul_f32 v[20:21], v[20:21], v[26:27]
	v_rcp_f32_e32 v16, v10
	v_mul_f32_e32 v10, 0xbfb8aa3b, v22
	v_exp_f32_e32 v12, v12
	v_lshlrev_b32_e32 v26, 16, v181
	v_and_b32_e32 v27, 0xffff0000, v181
	v_mul_f32_e32 v11, 0xbfb8aa3b, v23
	v_exp_f32_e32 v10, v10
	v_exp_f32_e32 v11, v11
	v_add_f32_e32 v12, 1.0, v12
	v_rcp_f32_e32 v17, v12
	v_add_f32_e32 v10, 1.0, v10
	v_add_f32_e32 v11, 1.0, v11
	v_rcp_f32_e32 v10, v10
	v_rcp_f32_e32 v11, v11
	v_pk_mul_f32 v[16:17], v[16:17], v[26:27]
	v_lshlrev_b32_e32 v12, 16, v183
	v_and_b32_e32 v13, 0xffff0000, v183
	v_pk_mul_f32 v[22:23], v[10:11], v[12:13]
	v_cvt_pk_bf16_f32 v11, v16, v17
	v_mad_i64_i32 v[16:17], s[0:1], v18, s19, v[124:125]
	v_cvt_pk_bf16_f32 v10, v24, v25
	v_cvt_pk_bf16_f32 v12, v20, v21
	v_cvt_pk_bf16_f32 v13, v22, v23
	v_lshl_add_u64 v[16:17], v[16:17], 0, v[122:123]
	global_store_dwordx4 v[16:17], v[10:13], off
	s_waitcnt vmcnt(4)
	s_nop 0
	s_waitcnt vmcnt(2)
	v_pk_add_f32 v[10:11], v[2:3], v[184:185]
	v_lshl_add_u64 v[2:3], v[14:15], 0, v[114:115]
	v_pk_add_f32 v[18:19], v[6:7], v[188:189]
	v_pk_add_f32 v[12:13], v[4:5], v[186:187]
	s_waitcnt vmcnt(1)
	v_mul_f32_e32 v3, 0xbfb8aa3b, v10
	v_exp_f32_e32 v3, v3
	v_mul_f32_e32 v2, 0xbfb8aa3b, v18
	v_exp_f32_e32 v2, v2
	v_pk_add_f32 v[8:9], v[8:9], v[190:191]
	v_add_f32_e32 v3, 1.0, v3
	v_rcp_f32_e32 v10, v3
	v_mul_f32_e32 v3, 0xbfb8aa3b, v19
	v_exp_f32_e32 v3, v3
	v_add_f32_e32 v2, 1.0, v2
	v_rcp_f32_e32 v2, v2
	v_add_f32_e32 v3, 1.0, v3
	v_rcp_f32_e32 v3, v3
	v_lshlrev_b32_e32 v14, 16, v192
	v_and_b32_e32 v15, 0xffff0000, v192
	v_mul_f32_e32 v4, 0xbfb8aa3b, v11
	v_exp_f32_e32 v4, v4
	v_pk_mul_f32 v[2:3], v[2:3], v[14:15]
	v_lshlrev_b32_e32 v14, 16, v194
	v_and_b32_e32 v15, 0xffff0000, v194
	v_add_f32_e32 v4, 1.0, v4
	v_rcp_f32_e32 v11, v4
	v_mul_f32_e32 v4, 0xbfb8aa3b, v8
	v_exp_f32_e32 v4, v4
	v_mul_f32_e32 v6, 0xbfb8aa3b, v9
	v_pk_mul_f32 v[10:11], v[10:11], v[14:15]
	v_lshlrev_b32_e32 v14, 16, v193
	v_add_f32_e32 v4, 1.0, v4
	v_rcp_f32_e32 v8, v4
	v_mul_f32_e32 v4, 0xbfb8aa3b, v12
	v_and_b32_e32 v15, 0xffff0000, v193
	v_mul_f32_e32 v5, 0xbfb8aa3b, v13
	v_exp_f32_e32 v4, v4
	v_exp_f32_e32 v6, v6
	v_exp_f32_e32 v5, v5
	v_cvt_pk_bf16_f32 v2, v2, v3
	v_add_f32_e32 v4, 1.0, v4
	v_add_f32_e32 v6, 1.0, v6
	v_add_f32_e32 v5, 1.0, v5
	v_rcp_f32_e32 v4, v4
	v_rcp_f32_e32 v9, v6
	v_rcp_f32_e32 v5, v5
	v_lshlrev_b32_e32 v6, 16, v195
	v_and_b32_e32 v7, 0xffff0000, v195
	v_pk_mul_f32 v[8:9], v[8:9], v[14:15]
	v_pk_mul_f32 v[6:7], v[4:5], v[6:7]
	v_cvt_pk_bf16_f32 v3, v8, v9
	v_cvt_pk_bf16_f32 v4, v10, v11
	v_cvt_pk_bf16_f32 v5, v6, v7
	global_store_dwordx4 v[16:17], v[2:5], off offset:256
	s_cbranch_vccnz .LBB0_284
	s_andn2_b64 vcc, exec, s[10:11]
	s_cbranch_vccnz .LBB0_283
	s_barrier
	s_branch .LBB0_283
